# stack6 + tagged-granule row-stat exchange in P4 (2x) and P8: no slot ack wait, no arrival atomic, no middle barrier
# baseline (speedup 1.0000x reference)
.LBB0_614:
	s_or_b64 exec, exec, s[8:9]
	v_lshl_add_u32 v155, v165, 4, v164
	s_waitcnt lgkmcnt(0)
	s_barrier
	v_and_or_b32 v198, v155, 31, s34
	v_cmp_gt_i32_e64 s[8:9], 32, v155
	v_lshl_add_u32 v200, v198, 4, 0
	v_lshl_add_u32 v164, s2, 8, v198
	s_and_saveexec_b64 s[84:85], s[8:9]
	s_cbranch_execz .LBB0_636
	v_add_u32_e32 v165, 0x20200, v200
	ds_read_b128 v[178:181], v165
	v_ashrrev_i32_e32 v165, 31, v164
	s_ashr_i32 s81, s80, 31
	s_waitcnt lgkmcnt(0)
	v_mov_b32_e32 v166, v179
	v_mov_b32_e32 v167, v180
	v_mov_b32_e32 v179, v181
	v_pk_add_f32 v[166:167], v[166:167], v[178:179]
	v_pk_add_f32 v[166:167], v[166:167], v[166:167] op_sel:[0,1] op_sel_hi:[1,0]
	v_lshl_add_u32 v199, v198, 2, 0
	s_add_u32 s98, s18, 0x3d00000
	s_addc_u32 s99, s19, 0
	v_lshlrev_b64 v[236:237], 6, v[164:165]
	v_lshl_add_u64 v[236:237], s[98:99], 0, v[236:237]
	s_lshl_b32 s100, s80, 3
	s_mov_b32 s101, 0
	v_mov_b32_e32 v167, 0x5eed7a61
	v_lshl_add_u64 v[238:239], s[100:101], 0, v[236:237]
	global_store_dwordx2 v[238:239], v[166:167], off sc1
	s_mov_b32 s100, 0
	s_sleep 12
.Lx41_spin:
	global_load_dwordx4 v[220:223], v[236:237], off sc1
	global_load_dwordx4 v[224:227], v[236:237], off offset:16 sc1
	global_load_dwordx4 v[228:231], v[236:237], off offset:32 sc1
	global_load_dwordx4 v[232:235], v[236:237], off offset:48 sc1
	s_waitcnt vmcnt(0)
	v_cmp_eq_u32_e32 vcc, 0x5eed7a61, v221
	s_and_b64 s[98:99], vcc, exec
	v_cmp_eq_u32_e32 vcc, 0x5eed7a61, v223
	s_and_b64 s[98:99], s[98:99], vcc
	v_cmp_eq_u32_e32 vcc, 0x5eed7a61, v225
	s_and_b64 s[98:99], s[98:99], vcc
	v_cmp_eq_u32_e32 vcc, 0x5eed7a61, v227
	s_and_b64 s[98:99], s[98:99], vcc
	v_cmp_eq_u32_e32 vcc, 0x5eed7a61, v229
	s_and_b64 s[98:99], s[98:99], vcc
	v_cmp_eq_u32_e32 vcc, 0x5eed7a61, v231
	s_and_b64 s[98:99], s[98:99], vcc
	v_cmp_eq_u32_e32 vcc, 0x5eed7a61, v233
	s_and_b64 s[98:99], s[98:99], vcc
	v_cmp_eq_u32_e32 vcc, 0x5eed7a61, v235
	s_and_b64 s[98:99], s[98:99], vcc
	s_cmp_eq_u64 s[98:99], exec
	s_cbranch_scc1 .Lx41_done
	s_sleep 4
	s_add_u32 s100, s100, 1
	s_cmp_lt_u32 s100, 0x4000
	s_cbranch_scc1 .Lx41_spin
.Lx41_done:
	v_add_f32_e32 v165, 0, v220
	v_add_f32_e32 v165, v165, v222
	v_add_f32_e32 v165, v165, v224
	v_add_f32_e32 v165, v165, v226
	v_add_f32_e32 v165, v165, v228
	v_add_f32_e32 v165, v165, v230
	v_add_f32_e32 v165, v165, v232
	v_add_f32_e32 v155, v165, v234
	v_fmamk_f32 v155, v155, 0x3a000000, v197
	v_cmp_gt_f32_e32 vcc, s95, v155
	v_mul_f32_e32 v165, 0x4b800000, v155
	s_nop 0
	v_cndmask_b32_e32 v155, v155, v165, vcc
	v_rsq_f32_e32 v155, v155
	s_nop 0
	v_mul_f32_e32 v165, 0x45800000, v155
	v_cndmask_b32_e32 v155, v155, v165, vcc
	v_add_u32_e32 v165, 0x21200, v199
	ds_write_b32 v165, v155

.LBB0_652:
	s_or_b64 exec, exec, s[82:83]
	s_waitcnt lgkmcnt(0)
	s_barrier
	s_and_saveexec_b64 s[6:7], s[8:9]
	s_cbranch_execz .LBB0_674
	v_add_u32_e32 v130, 0x20200, v200
	s_waitcnt lgkmcnt(0)
	ds_read_b128 v[130:133], v130
	v_ashrrev_i32_e32 v165, 31, v164
	s_ashr_i32 s81, s80, 31
	s_waitcnt lgkmcnt(0)
	v_mov_b32_e32 v134, v131
	v_mov_b32_e32 v135, v132
	v_mov_b32_e32 v131, v133
	v_pk_add_f32 v[130:131], v[134:135], v[130:131]
	v_pk_add_f32 v[130:131], v[130:131], v[130:131] op_sel:[0,1] op_sel_hi:[1,0]
	s_lshl_b32 s2, s2, 8
	s_add_u32 s98, s18, 0x3d80000
	s_addc_u32 s99, s19, 0
	v_lshlrev_b64 v[236:237], 6, v[164:165]
	v_lshl_add_u64 v[236:237], s[98:99], 0, v[236:237]
	s_lshl_b32 s100, s80, 3
	s_mov_b32 s101, 0
	v_mov_b32_e32 v131, 0x5eed7a61
	v_lshl_add_u64 v[238:239], s[100:101], 0, v[236:237]
	global_store_dwordx2 v[238:239], v[130:131], off sc1
	s_mov_b32 s100, 0
	s_sleep 12

.Lx42_done:
	v_add_f32_e32 v132, 0, v220
	v_add_f32_e32 v132, v132, v222
	v_add_f32_e32 v132, v132, v224
	v_add_f32_e32 v132, v132, v226
	v_add_f32_e32 v132, v132, v228
	v_add_f32_e32 v132, v132, v230
	v_add_f32_e32 v132, v132, v232
	v_add_f32_e32 v130, v132, v234
	v_fmamk_f32 v130, v130, 0x3a000000, v197
	v_cmp_gt_f32_e32 vcc, s95, v130
	v_mul_f32_e32 v131, 0x4b800000, v130
	s_nop 0
	v_cndmask_b32_e32 v130, v130, v131, vcc
	v_rsq_f32_e32 v130, v130
	s_nop 0
	v_mul_f32_e32 v131, 0x45800000, v130
	v_cndmask_b32_e32 v130, v130, v131, vcc
	v_add_u32_e32 v131, 0x21200, v199
	ds_write_b32 v131, v130

.LBB0_984:
	s_or_b64 exec, exec, s[4:5]
	v_lshl_add_u32 v141, v139, 4, v138
	s_waitcnt lgkmcnt(0)
	s_barrier
	s_waitcnt lgkmcnt(0)
	v_and_or_b32 v140, v141, 31, s64
	v_cmp_gt_i32_e64 s[6:7], 32, v141
	v_lshl_add_u32 v136, s42, 8, v140
	s_and_saveexec_b64 s[4:5], s[6:7]
	s_cbranch_execz .LBB0_1006
	v_lshl_add_u32 v137, v140, 4, 0
	v_add_u32_e32 v137, 0x20200, v137
	ds_read_b128 v[142:145], v137
	v_ashrrev_i32_e32 v137, 31, v136
	s_ashr_i32 s41, s40, 31
	s_waitcnt lgkmcnt(0)
	v_mov_b32_e32 v146, v143
	v_mov_b32_e32 v147, v144
	v_mov_b32_e32 v143, v145
	v_pk_add_f32 v[142:143], v[146:147], v[142:143]
	v_pk_add_f32 v[142:143], v[142:143], v[142:143] op_sel:[0,1] op_sel_hi:[1,0]
	s_add_u32 s98, s18, 0x3e00000
	s_addc_u32 s99, s19, 0
	v_lshlrev_b64 v[144:145], 6, v[136:137]
	v_lshl_add_u64 v[144:145], s[98:99], 0, v[144:145]
	s_lshl_b32 s100, s40, 3
	s_mov_b32 s101, 0
	v_mov_b32_e32 v143, 0x5eed7a61
	v_lshl_add_u64 v[146:147], s[100:101], 0, v[144:145]
	global_store_dwordx2 v[146:147], v[142:143], off sc1
	s_mov_b32 s100, 0
	s_sleep 12
.Lx8_spin:
	global_load_dwordx4 v[200:203], v[144:145], off sc1
	global_load_dwordx4 v[204:207], v[144:145], off offset:16 sc1
	global_load_dwordx4 v[208:211], v[144:145], off offset:32 sc1
	global_load_dwordx4 v[212:215], v[144:145], off offset:48 sc1
	s_waitcnt vmcnt(0)
	v_cmp_eq_u32_e32 vcc, 0x5eed7a61, v201
	s_and_b64 s[98:99], vcc, exec
	v_cmp_eq_u32_e32 vcc, 0x5eed7a61, v203
	s_and_b64 s[98:99], s[98:99], vcc
	v_cmp_eq_u32_e32 vcc, 0x5eed7a61, v205
	s_and_b64 s[98:99], s[98:99], vcc
	v_cmp_eq_u32_e32 vcc, 0x5eed7a61, v207
	s_and_b64 s[98:99], s[98:99], vcc
	v_cmp_eq_u32_e32 vcc, 0x5eed7a61, v209
	s_and_b64 s[98:99], s[98:99], vcc
	v_cmp_eq_u32_e32 vcc, 0x5eed7a61, v211
	s_and_b64 s[98:99], s[98:99], vcc
	v_cmp_eq_u32_e32 vcc, 0x5eed7a61, v213
	s_and_b64 s[98:99], s[98:99], vcc
	v_cmp_eq_u32_e32 vcc, 0x5eed7a61, v215
	s_and_b64 s[98:99], s[98:99], vcc
	s_cmp_eq_u64 s[98:99], exec
	s_cbranch_scc1 .Lx8_done
	s_sleep 4
	s_add_u32 s100, s100, 1
	s_cmp_lt_u32 s100, 0x4000
	s_cbranch_scc1 .Lx8_spin
.Lx8_done:
	v_add_f32_e32 v137, 0, v200
	v_add_f32_e32 v137, v137, v202
	v_add_f32_e32 v137, v137, v204
	v_add_f32_e32 v137, v137, v206
	v_add_f32_e32 v137, v137, v208
	v_add_f32_e32 v137, v137, v210
	v_add_f32_e32 v137, v137, v212
	v_add_f32_e32 v136, v137, v214
	v_fmamk_f32 v136, v136, 0x3a000000, v160
	v_mul_f32_e32 v137, 0x4b800000, v136
	v_cmp_gt_f32_e32 vcc, s71, v136
	s_nop 1
	v_cndmask_b32_e32 v136, v136, v137, vcc
	v_rsq_f32_e32 v136, v136
	v_lshl_add_u32 v137, v140, 2, 0
	v_add_u32_e32 v137, 0x21200, v137
	v_mul_f32_e32 v140, 0x45800000, v136
	v_cndmask_b32_e32 v136, v136, v140, vcc
	ds_write_b32 v137, v136
